# prologue loops batched plus nt hint on the idle-slot bf16 weight stores (never re-read from the local L2)
# baseline (speedup 1.0000x reference)
; #define LAS __attribute__((address_space(3)))
; __device__ __forceinline__ void transpose_item(const float* W, int K, int N, const float* g0, const float* g1, bf16_t* WT, LAS unsigned* T, int item, int lane, bool gate_up_interleave = false, bool rope_heads = false) {
;     ...
;     for (int it = 0; it < 16; ++it) {
;         const int n = 8 * it + (lane >> 3);
;         const u32x4 o = *(const LAS u32x4*)(T + n * PD + 4 * c);
;         const int nd = (rope_heads && nb >= 24 && nb < 34) ? ((n < 64) ? (8 * (n >> 2) + (n & 3)) : (8 * ((n - 64) >> 2) + 4 + (n & 3))) : n;
;         *(u32x4*)(WT + (size_t)(dn0 + nd) * K + k0 + 8 * c) = o;
;     }
.LBB0_299:
	v_add_u32_e32 v14, s14, v14
	v_ashrrev_i32_e32 v15, 31, v14
	v_mul_lo_u32 v16, s40, v15
	v_mul_lo_u32 v17, s41, v14
	v_mad_u64_u32 v[14:15], s[0:1], s40, v14, 0
	v_add3_u32 v15, v15, v16, v17
	s_add_i32 s50, s50, 4
	s_add_i32 s48, s48, 32
	v_lshl_add_u64 v[14:15], v[14:15], 1, v[6:7]
	v_add_u32_e32 v9, 64, v9
	s_cmpk_lg_i32 s48, 0x80
	v_add_u32_e32 v8, 0x1200, v8
	s_waitcnt lgkmcnt(0)
	global_store_dwordx4 v[14:15], v[2:5], off nt
	s_cbranch_scc0 .LBB0_274

; #define LAS __attribute__((address_space(3)))
; __device__ __forceinline__ void transpose_item(const float* W, int K, int N, const float* g0, const float* g1, bf16_t* WT, LAS unsigned* T, int item, int lane, bool gate_up_interleave = false, bool rope_heads = false) {
;     ...
;     for (int it = 0; it < 16; ++it) {
;         const int n = 8 * it + (lane >> 3);
;         const u32x4 o = *(const LAS u32x4*)(T + n * PD + 4 * c);
;         const int nd = (rope_heads && nb >= 24 && nb < 34) ? ((n < 64) ? (8 * (n >> 2) + (n & 3)) : (8 * ((n - 64) >> 2) + 4 + (n & 3))) : n;
;         *(u32x4*)(WT + (size_t)(dn0 + nd) * K + k0 + 8 * c) = o;
;     }
.LBB0_305:
	v_add_u32_e32 v15, s14, v15
	v_ashrrev_i32_e32 v16, 31, v15
	v_mul_lo_u32 v18, s40, v16
	v_mul_lo_u32 v19, s41, v15
	v_mad_u64_u32 v[16:17], s[60:61], s40, v15, 0
	v_add3_u32 v17, v17, v18, v19
	v_lshl_add_u64 v[16:17], v[16:17], 1, v[6:7]
	s_waitcnt lgkmcnt(0)
	global_store_dwordx4 v[16:17], v[2:5], off nt
	ds_read_b128 v[2:5], v8 offset:1152
	s_and_b64 vcc, exec, s[0:1]
	s_cbranch_vccnz .LBB0_310
	s_cmp_lt_u32 s50, 8
	s_mov_b64 s[60:61], -1
	s_cbranch_scc1 .LBB0_308
	v_or_b32_e32 v15, s51, v38
	v_lshlrev_b32_e32 v15, 1, v15
	v_and_b32_e32 v15, 0xd8, v15
	v_add_u32_e32 v15, v15, v36
	s_mov_b64 s[60:61], 0

; #define LAS __attribute__((address_space(3)))
; __device__ __forceinline__ void transpose_item(const float* W, int K, int N, const float* g0, const float* g1, bf16_t* WT, LAS unsigned* T, int item, int lane, bool gate_up_interleave = false, bool rope_heads = false) {
;     ...
;     for (int it = 0; it < 16; ++it) {
;         const int n = 8 * it + (lane >> 3);
;         const u32x4 o = *(const LAS u32x4*)(T + n * PD + 4 * c);
;         const int nd = (rope_heads && nb >= 24 && nb < 34) ? ((n < 64) ? (8 * (n >> 2) + (n & 3)) : (8 * ((n - 64) >> 2) + 4 + (n & 3))) : n;
;         *(u32x4*)(WT + (size_t)(dn0 + nd) * K + k0 + 8 * c) = o;
;     }
.LBB0_311:
	v_add_u32_e32 v15, s14, v15
	v_ashrrev_i32_e32 v16, 31, v15
	v_mul_lo_u32 v18, s40, v16
	v_mul_lo_u32 v19, s41, v15
	v_mad_u64_u32 v[16:17], s[60:61], s40, v15, 0
	v_add3_u32 v17, v17, v18, v19
	v_lshl_add_u64 v[16:17], v[16:17], 1, v[6:7]
	s_waitcnt lgkmcnt(0)
	global_store_dwordx4 v[16:17], v[2:5], off nt
	ds_read_b128 v[2:5], v8 offset:2304
	s_and_b64 vcc, exec, s[0:1]
	s_cbranch_vccnz .LBB0_316
	s_cmp_lt_u32 s50, 8
	s_mov_b64 s[60:61], -1
	s_cbranch_scc1 .LBB0_314
	v_or_b32_e32 v15, s51, v39
	v_lshlrev_b32_e32 v15, 1, v15
	v_and_b32_e32 v15, 0xe8, v15
	v_add_u32_e32 v15, v15, v36
	s_mov_b64 s[60:61], 0

; #define LAS __attribute__((address_space(3)))
; __device__ __forceinline__ void transpose_item(const float* W, int K, int N, const float* g0, const float* g1, bf16_t* WT, LAS unsigned* T, int item, int lane, bool gate_up_interleave = false, bool rope_heads = false) {
;     ...
;     for (int it = 0; it < 16; ++it) {
;         const int n = 8 * it + (lane >> 3);
;         const u32x4 o = *(const LAS u32x4*)(T + n * PD + 4 * c);
;         const int nd = (rope_heads && nb >= 24 && nb < 34) ? ((n < 64) ? (8 * (n >> 2) + (n & 3)) : (8 * ((n - 64) >> 2) + 4 + (n & 3))) : n;
;         *(u32x4*)(WT + (size_t)(dn0 + nd) * K + k0 + 8 * c) = o;
;     }
.LBB0_317:
	v_add_u32_e32 v15, s14, v15
	v_ashrrev_i32_e32 v16, 31, v15
	v_mul_lo_u32 v18, s40, v16
	v_mul_lo_u32 v19, s41, v15
	v_mad_u64_u32 v[16:17], s[60:61], s40, v15, 0
	v_add3_u32 v17, v17, v18, v19
	v_lshl_add_u64 v[16:17], v[16:17], 1, v[6:7]
	s_waitcnt lgkmcnt(0)
	global_store_dwordx4 v[16:17], v[2:5], off nt
	ds_read_b128 v[2:5], v8 offset:3456
	s_and_b64 vcc, exec, s[0:1]
	s_cbranch_vccnz .LBB0_298
	s_cmp_lt_u32 s50, 8
	s_mov_b64 s[0:1], -1
	s_cbranch_scc1 .LBB0_320
	v_or_b32_e32 v14, s51, v40
	v_lshlrev_b32_e32 v14, 1, v14
	v_and_b32_e32 v14, 0xf8, v14
	v_add_u32_e32 v14, v14, v36
	s_mov_b64 s[0:1], 0
